# last phase: consumer-less prompt row-sum loop skipped in the final finalize
# speedup vs baseline: 1.0006x; 1.0006x over previous
.Lfz_legacy:
	s_mov_b32 s0, 0
	v_writelane_b32 v244, s0, 2
	v_readlane_b32 s0, v243, 24
	v_writelane_b32 v244, s0, 6
	v_writelane_b32 v244, s99, 7
	s_movk_i32 s0, 0x4000
	v_readlane_b32 s12, v243, 23
